# attention QK: counted LDS waits merged pairwise (6 fewer s_waitcnt per tile)
# speedup vs baseline: 1.0133x; 1.0033x over previous
; DI void attn_item(const Params& p, int item, char* smem) {
;     ...
; #pragma unroll
;     for (int d0 = 0; d0 < 6; ++d0) {
;       const bf16x8 a0 = *(const bf16x8*)(Kc + r32 * KSL + d0 * 16 + hi * 8);
;       const bf16x8 a1 = *(const bf16x8*)(Kc + (32 + r32) * KSL + d0 * 16 + hi * 8);
;       p0 = __builtin_amdgcn_mfma_f32_32x32x16_bf16(a0, qr[d0], p0, 0, 0, 0);
;       p1 = __builtin_amdgcn_mfma_f32_32x32x16_bf16(a1, qr[d0], p1, 0, 0, 0);
;     }
;     float mx = p0[0];
; #pragma unroll
;     for (int i = 1; i < 16; ++i) mx = fmaxf(mx, p0[i]);
; #pragma unroll
;     for (int i = 0; i < 16; ++i) mx = fmaxf(mx, p1[i]);
;     { auto rr = __builtin_amdgcn_permlane32_swap(__float_as_uint(mx), __float_as_uint(mx), false, false);
;       mx = fmaxf(__uint_as_float(rr[0]), __uint_as_float(rr[1])); }
;     if (!__all(mx - mrun <= 8.f)) {
;       const float mn = fmaxf(mrun, mx);
;       const float alpha = __builtin_amdgcn_exp2f(mrun - mn);
;       mrun = mn; lrun *= alpha;
; #pragma unroll
;       for (int i = 0; i < 16; ++i) { o0[i] *= alpha; o1[i] *= alpha; }
;     }
;     float ps = 0.f;
; #pragma unroll
;     for (int i = 0; i < 16; ++i) { p0[i] = __builtin_amdgcn_exp2f(p0[i] - mrun); ps += p0[i]; }
; #pragma unroll
;     for (int i = 0; i < 16; ++i) { p1[i] = __builtin_amdgcn_exp2f(p1[i] - mrun); ps += p1[i]; }
;     lrun += ps;
.LBB0_531:
	ds_read_b128 v[164:167], v154
	ds_read_b128 v[168:171], v154 offset:32
	ds_read_b128 v[172:175], v154 offset:64
	ds_read_b128 v[176:179], v154 offset:96
	ds_read_b128 v[180:183], v154 offset:128
	ds_read_b128 v[184:187], v154 offset:160
	ds_read_b128 v[188:191], v154 offset:6656
	ds_read_b128 v[158:161], v154 offset:6688
	ds_read_b128 v[192:195], v154 offset:6720
	ds_read_b128 v[212:215], v154 offset:6752
	ds_read_b128 v[216:219], v154 offset:6784
	ds_read_b128 v[10:13], v154 offset:6816
	s_waitcnt lgkmcnt(10)
	v_mfma_f32_32x32x16_bf16 v[64:79], v[164:167], v[80:83], v[196:211]
	v_mfma_f32_32x32x16_bf16 v[64:79], v[168:171], v[84:87], v[64:79]
	s_waitcnt lgkmcnt(8)
	v_mfma_f32_32x32x16_bf16 v[64:79], v[172:175], v[88:91], v[64:79]
	v_mfma_f32_32x32x16_bf16 v[64:79], v[176:179], v[92:95], v[64:79]
	s_waitcnt lgkmcnt(6)
	v_mfma_f32_32x32x16_bf16 v[64:79], v[180:183], v[96:99], v[64:79]
	v_mfma_f32_32x32x16_bf16 v[64:79], v[184:187], v[100:103], v[64:79]
	s_waitcnt lgkmcnt(4)
	v_mfma_f32_32x32x16_bf16 v[48:63], v[188:191], v[80:83], v[196:211]
	v_mfma_f32_32x32x16_bf16 v[48:63], v[158:161], v[84:87], v[48:63]
	s_nop 8
	v_exp_f32_e32 v168, v64
	v_exp_f32_e32 v169, v65
	v_exp_f32_e32 v170, v66
	v_exp_f32_e32 v171, v67
	v_exp_f32_e32 v172, v68
	v_exp_f32_e32 v173, v69
	v_exp_f32_e32 v174, v70
	v_exp_f32_e32 v175, v71
	s_waitcnt lgkmcnt(2)
	v_mfma_f32_32x32x16_bf16 v[48:63], v[192:195], v[88:91], v[48:63]
	v_mfma_f32_32x32x16_bf16 v[48:63], v[212:215], v[92:95], v[48:63]
	v_exp_f32_e32 v176, v72
	v_exp_f32_e32 v177, v73
	v_exp_f32_e32 v178, v74
	v_exp_f32_e32 v179, v75
	v_exp_f32_e32 v180, v76
	v_exp_f32_e32 v181, v77
	v_exp_f32_e32 v182, v78
	v_exp_f32_e32 v183, v79
	s_waitcnt lgkmcnt(0)
	v_mfma_f32_32x32x16_bf16 v[48:63], v[216:219], v[96:99], v[48:63]
	v_mfma_f32_32x32x16_bf16 v[48:63], v[10:13], v[100:103], v[48:63]
	v_add_f32_e32 v0, v168, v169
	v_add_f32_e32 v0, v170, v0
	v_add_f32_e32 v0, v171, v0
	v_add_f32_e32 v0, v172, v0
	v_add_f32_e32 v0, v173, v0
	v_add_f32_e32 v0, v174, v0
	v_add_f32_e32 v0, v175, v0
	v_add_f32_e32 v0, v176, v0
	v_add_f32_e32 v0, v177, v0
	v_add_f32_e32 v0, v178, v0
	v_add_f32_e32 v0, v179, v0
	v_add_f32_e32 v0, v180, v0
	v_add_f32_e32 v0, v181, v0
	v_add_f32_e32 v0, v182, v0
	v_add_f32_e32 v0, v183, v0
	v_exp_f32_e32 v184, v48
	v_exp_f32_e32 v185, v49
	v_exp_f32_e32 v186, v50
	v_exp_f32_e32 v187, v51
	v_exp_f32_e32 v188, v52
	v_exp_f32_e32 v189, v53
	v_exp_f32_e32 v190, v54
	v_exp_f32_e32 v191, v55
	v_exp_f32_e32 v158, v56
	v_exp_f32_e32 v159, v57
	v_exp_f32_e32 v160, v58
	v_exp_f32_e32 v161, v59
	v_exp_f32_e32 v164, v60
	v_exp_f32_e32 v165, v61
	v_exp_f32_e32 v166, v62
	v_exp_f32_e32 v167, v63
	v_add_f32_e32 v0, v184, v0
	v_add_f32_e32 v0, v185, v0
	v_add_f32_e32 v0, v186, v0
	v_add_f32_e32 v0, v187, v0
	v_add_f32_e32 v0, v188, v0
	v_add_f32_e32 v0, v189, v0
	v_add_f32_e32 v0, v190, v0
	v_add_f32_e32 v0, v191, v0
	v_add_f32_e32 v0, v158, v0
	v_add_f32_e32 v0, v159, v0
	v_add_f32_e32 v0, v160, v0
	v_add_f32_e32 v0, v161, v0
	v_add_f32_e32 v0, v164, v0
	v_add_f32_e32 v0, v165, v0
	v_add_f32_e32 v0, v166, v0
	v_add_f32_e32 v0, v167, v0
	v_cmp_ge_f32_e32 vcc, s98, v0
	s_cmp_eq_u64 vcc, exec
	s_cbranch_scc1 .LBB0_533
; DI void attn_item(const Params& p, int item, char* smem) {
;     ...
;     { auto rr = __builtin_amdgcn_permlane32_swap(__float_as_uint(mx), __float_as_uint(mx), false, false);
;       mx = fmaxf(__uint_as_float(rr[0]), __uint_as_float(rr[1])); }
;     if (!__all(mx - mrun <= 8.f)) {
;       const float mn = fmaxf(mrun, mx);
;       const float alpha = __builtin_amdgcn_exp2f(mrun - mn);
;       mrun = mn; lrun *= alpha;
; #pragma unroll
;       for (int i = 0; i < 16; ++i) { o0[i] *= alpha; o1[i] *= alpha; }
;     }
;     float ps = 0.f;
; #pragma unroll
;     for (int i = 0; i < 16; ++i) { p0[i] = __builtin_amdgcn_exp2f(p0[i] - mrun); ps += p0[i]; }
; #pragma unroll
;     for (int i = 0; i < 16; ++i) { p1[i] = __builtin_amdgcn_exp2f(p1[i] - mrun); ps += p1[i]; }
	v_max_f32_e32 v10, v64, v65
	v_max3_f32 v10, v10, v66, v67
	v_max3_f32 v10, v10, v68, v69
	v_max3_f32 v10, v10, v70, v71
	v_max3_f32 v10, v10, v72, v73
	v_max3_f32 v10, v10, v74, v75
	v_max3_f32 v10, v10, v76, v77
	v_max3_f32 v10, v10, v78, v79
	v_max3_f32 v10, v10, v48, v49
	v_max3_f32 v10, v10, v50, v51
	v_max3_f32 v10, v10, v52, v53
	v_max3_f32 v10, v10, v54, v55
	v_max3_f32 v10, v10, v56, v57
	v_max3_f32 v10, v10, v58, v59
	v_max3_f32 v10, v10, v60, v61
	v_max3_f32 v10, v10, v62, v63
	v_mov_b32_e32 v11, v10
	s_nop 1
	v_permlane32_swap_b32_e32 v10, v11
	v_max_f32_e32 v10, v10, v11
	v_max_f32_e32 v11, s99, v10
	v_max_f32_e32 v10, 0, v11
	s_mov_b32 s98, 0x46000000
	v_exp_f32_e64 v10, -v10
	s_mov_b32 s99, 0
	v_sub_f32_e32 v196, v196, v11
	v_mul_f32_e32 v157, v157, v10
	v_pk_mul_f32 v[46:47], v[46:47], v[10:11] op_sel_hi:[1,0]
	v_pk_mul_f32 v[44:45], v[44:45], v[10:11] op_sel_hi:[1,0]
	v_pk_mul_f32 v[42:43], v[42:43], v[10:11] op_sel_hi:[1,0]
	v_pk_mul_f32 v[40:41], v[40:41], v[10:11] op_sel_hi:[1,0]
	v_pk_mul_f32 v[38:39], v[38:39], v[10:11] op_sel_hi:[1,0]
	v_pk_mul_f32 v[36:37], v[36:37], v[10:11] op_sel_hi:[1,0]
	v_pk_mul_f32 v[34:35], v[34:35], v[10:11] op_sel_hi:[1,0]
	v_pk_mul_f32 v[32:33], v[32:33], v[10:11] op_sel_hi:[1,0]
	v_pk_mul_f32 v[30:31], v[30:31], v[10:11] op_sel_hi:[1,0]
	v_pk_mul_f32 v[28:29], v[28:29], v[10:11] op_sel_hi:[1,0]
	v_pk_mul_f32 v[26:27], v[26:27], v[10:11] op_sel_hi:[1,0]
	v_pk_mul_f32 v[24:25], v[24:25], v[10:11] op_sel_hi:[1,0]
	v_pk_mul_f32 v[22:23], v[22:23], v[10:11] op_sel_hi:[1,0]
	v_pk_mul_f32 v[20:21], v[20:21], v[10:11] op_sel_hi:[1,0]
	v_pk_mul_f32 v[18:19], v[18:19], v[10:11] op_sel_hi:[1,0]
	v_pk_mul_f32 v[16:17], v[16:17], v[10:11] op_sel_hi:[1,0]
	v_mov_b32_e32 v197, v196
	v_mov_b32_e32 v198, v196
	v_mov_b32_e32 v199, v196
	v_mov_b32_e32 v200, v196
	v_mov_b32_e32 v201, v196
	v_mov_b32_e32 v202, v196
	v_mov_b32_e32 v203, v196
	v_mov_b32_e32 v204, v196
	v_mov_b32_e32 v205, v196
	v_mov_b32_e32 v206, v196
	v_mov_b32_e32 v207, v196
	v_mov_b32_e32 v208, v196
	v_mov_b32_e32 v209, v196
	v_mov_b32_e32 v210, v196
	v_mov_b32_e32 v211, v196
	v_sub_f32_e32 v64, v64, v11
	v_sub_f32_e32 v65, v65, v11
	v_sub_f32_e32 v66, v66, v11
	v_sub_f32_e32 v67, v67, v11
	v_sub_f32_e32 v68, v68, v11
	v_sub_f32_e32 v69, v69, v11
	v_sub_f32_e32 v70, v70, v11
	v_sub_f32_e32 v71, v71, v11
	v_sub_f32_e32 v72, v72, v11
	v_sub_f32_e32 v73, v73, v11
	v_sub_f32_e32 v74, v74, v11
	v_sub_f32_e32 v75, v75, v11
	v_sub_f32_e32 v76, v76, v11
	v_sub_f32_e32 v77, v77, v11
	v_sub_f32_e32 v78, v78, v11
	v_sub_f32_e32 v79, v79, v11
	v_sub_f32_e32 v48, v48, v11
	v_sub_f32_e32 v49, v49, v11
	v_sub_f32_e32 v50, v50, v11
	v_sub_f32_e32 v51, v51, v11
	v_sub_f32_e32 v52, v52, v11
	v_sub_f32_e32 v53, v53, v11
	v_sub_f32_e32 v54, v54, v11
	v_sub_f32_e32 v55, v55, v11
	v_sub_f32_e32 v56, v56, v11
	v_sub_f32_e32 v57, v57, v11
	v_sub_f32_e32 v58, v58, v11
	v_sub_f32_e32 v59, v59, v11
	v_sub_f32_e32 v60, v60, v11
	v_sub_f32_e32 v61, v61, v11
	v_sub_f32_e32 v62, v62, v11
	v_sub_f32_e32 v63, v63, v11
	v_exp_f32_e32 v168, v64
	v_exp_f32_e32 v169, v65
	v_exp_f32_e32 v170, v66
	v_exp_f32_e32 v171, v67
	v_exp_f32_e32 v172, v68
	v_exp_f32_e32 v173, v69
	v_exp_f32_e32 v174, v70
	v_exp_f32_e32 v175, v71
	v_exp_f32_e32 v176, v72
	v_exp_f32_e32 v177, v73
	v_exp_f32_e32 v178, v74
	v_exp_f32_e32 v179, v75
	v_exp_f32_e32 v180, v76
	v_exp_f32_e32 v181, v77
	v_exp_f32_e32 v182, v78
	v_exp_f32_e32 v183, v79
	v_exp_f32_e32 v184, v48
	v_exp_f32_e32 v185, v49
	v_exp_f32_e32 v186, v50
	v_exp_f32_e32 v187, v51
	v_exp_f32_e32 v188, v52
	v_exp_f32_e32 v189, v53
	v_exp_f32_e32 v190, v54
	v_exp_f32_e32 v191, v55
	v_exp_f32_e32 v158, v56
	v_exp_f32_e32 v159, v57
	v_exp_f32_e32 v160, v58
	v_exp_f32_e32 v161, v59
	v_exp_f32_e32 v164, v60
	v_exp_f32_e32 v165, v61
	v_exp_f32_e32 v166, v62
	v_exp_f32_e32 v167, v63
	v_add_f32_e32 v0, v168, v169
	v_add_f32_e32 v0, v170, v0
	v_add_f32_e32 v0, v171, v0
	v_add_f32_e32 v0, v172, v0
	v_add_f32_e32 v0, v173, v0
	v_add_f32_e32 v0, v174, v0
	v_add_f32_e32 v0, v175, v0
	v_add_f32_e32 v0, v176, v0
	v_add_f32_e32 v0, v177, v0
	v_add_f32_e32 v0, v178, v0
	v_add_f32_e32 v0, v179, v0
	v_add_f32_e32 v0, v180, v0
	v_add_f32_e32 v0, v181, v0
	v_add_f32_e32 v0, v182, v0
	v_add_f32_e32 v0, v183, v0
	v_add_f32_e32 v0, v184, v0
	v_add_f32_e32 v0, v185, v0
	v_add_f32_e32 v0, v186, v0
	v_add_f32_e32 v0, v187, v0
	v_add_f32_e32 v0, v188, v0
	v_add_f32_e32 v0, v189, v0
	v_add_f32_e32 v0, v190, v0
	v_add_f32_e32 v0, v191, v0
	v_add_f32_e32 v0, v158, v0
	v_add_f32_e32 v0, v159, v0
	v_add_f32_e32 v0, v160, v0
	v_add_f32_e32 v0, v161, v0
	v_add_f32_e32 v0, v164, v0
	v_add_f32_e32 v0, v165, v0
	v_add_f32_e32 v0, v166, v0
	v_add_f32_e32 v0, v167, v0

; DI void attn_item(const Params& p, int item, char* smem) {
;     ...
; #pragma unroll
;     for (int d0 = 0; d0 < 6; ++d0) {
;       const bf16x8 a0 = *(const bf16x8*)(Kc + r32 * KSL + d0 * 16 + hi * 8);
;       const bf16x8 a1 = *(const bf16x8*)(Kc + (32 + r32) * KSL + d0 * 16 + hi * 8);
;       p0 = __builtin_amdgcn_mfma_f32_32x32x16_bf16(a0, qr[d0], p0, 0, 0, 0);
;       p1 = __builtin_amdgcn_mfma_f32_32x32x16_bf16(a1, qr[d0], p1, 0, 0, 0);
;     }
;     float mx = p0[0];
; #pragma unroll
;     for (int i = 1; i < 16; ++i) mx = fmaxf(mx, p0[i]);
; #pragma unroll
;     for (int i = 0; i < 16; ++i) mx = fmaxf(mx, p1[i]);
;     { auto rr = __builtin_amdgcn_permlane32_swap(__float_as_uint(mx), __float_as_uint(mx), false, false);
;       mx = fmaxf(__uint_as_float(rr[0]), __uint_as_float(rr[1])); }
;     if (!__all(mx - mrun <= 8.f)) {
;       const float mn = fmaxf(mrun, mx);
;       const float alpha = __builtin_amdgcn_exp2f(mrun - mn);
;       mrun = mn; lrun *= alpha;
; #pragma unroll
;       for (int i = 0; i < 16; ++i) { o0[i] *= alpha; o1[i] *= alpha; }
;     }
;     float ps = 0.f;
; #pragma unroll
;     for (int i = 0; i < 16; ++i) { p0[i] = __builtin_amdgcn_exp2f(p0[i] - mrun); ps += p0[i]; }
; #pragma unroll
;     for (int i = 0; i < 16; ++i) { p1[i] = __builtin_amdgcn_exp2f(p1[i] - mrun); ps += p1[i]; }
;     lrun += ps;
.LBB0_535:
	ds_read_b128 v[164:167], v154 offset:13312
	ds_read_b128 v[168:171], v154 offset:13344
	ds_read_b128 v[172:175], v154 offset:13376
	ds_read_b128 v[176:179], v154 offset:13408
	ds_read_b128 v[180:183], v154 offset:13440
	ds_read_b128 v[184:187], v154 offset:13472
	ds_read_b128 v[188:191], v154 offset:19968
	ds_read_b128 v[158:161], v154 offset:20000
	ds_read_b128 v[192:195], v154 offset:20032
	ds_read_b128 v[212:215], v154 offset:20064
	ds_read_b128 v[216:219], v154 offset:20096
	ds_read_b128 v[10:13], v154 offset:20128
	s_waitcnt lgkmcnt(10)
	v_mfma_f32_32x32x16_bf16 v[64:79], v[164:167], v[80:83], v[196:211]
	v_mfma_f32_32x32x16_bf16 v[64:79], v[168:171], v[84:87], v[64:79]
	s_waitcnt lgkmcnt(8)
	v_mfma_f32_32x32x16_bf16 v[64:79], v[172:175], v[88:91], v[64:79]
	v_mfma_f32_32x32x16_bf16 v[64:79], v[176:179], v[92:95], v[64:79]
	s_waitcnt lgkmcnt(6)
	v_mfma_f32_32x32x16_bf16 v[64:79], v[180:183], v[96:99], v[64:79]
	v_mfma_f32_32x32x16_bf16 v[64:79], v[184:187], v[100:103], v[64:79]
	s_waitcnt lgkmcnt(4)
	v_mfma_f32_32x32x16_bf16 v[48:63], v[188:191], v[80:83], v[196:211]
	v_mfma_f32_32x32x16_bf16 v[48:63], v[158:161], v[84:87], v[48:63]
	s_nop 8
	v_exp_f32_e32 v168, v64
	v_exp_f32_e32 v169, v65
	v_exp_f32_e32 v170, v66
	v_exp_f32_e32 v171, v67
	v_exp_f32_e32 v172, v68
	v_exp_f32_e32 v173, v69
	v_exp_f32_e32 v174, v70
	v_exp_f32_e32 v175, v71
	s_waitcnt lgkmcnt(2)
	v_mfma_f32_32x32x16_bf16 v[48:63], v[192:195], v[88:91], v[48:63]
	v_mfma_f32_32x32x16_bf16 v[48:63], v[212:215], v[92:95], v[48:63]
	v_exp_f32_e32 v176, v72
	v_exp_f32_e32 v177, v73
	v_exp_f32_e32 v178, v74
	v_exp_f32_e32 v179, v75
	v_exp_f32_e32 v180, v76
	v_exp_f32_e32 v181, v77
	v_exp_f32_e32 v182, v78
	v_exp_f32_e32 v183, v79
	s_waitcnt lgkmcnt(0)
	v_mfma_f32_32x32x16_bf16 v[48:63], v[216:219], v[96:99], v[48:63]
	v_mfma_f32_32x32x16_bf16 v[48:63], v[10:13], v[100:103], v[48:63]
	v_add_f32_e32 v0, v168, v169
	v_add_f32_e32 v0, v170, v0
	v_add_f32_e32 v0, v171, v0
	v_add_f32_e32 v0, v172, v0
	v_add_f32_e32 v0, v173, v0
	v_add_f32_e32 v0, v174, v0
	v_add_f32_e32 v0, v175, v0
	v_add_f32_e32 v0, v176, v0
	v_add_f32_e32 v0, v177, v0
	v_add_f32_e32 v0, v178, v0
	v_add_f32_e32 v0, v179, v0
	v_add_f32_e32 v0, v180, v0
	v_add_f32_e32 v0, v181, v0
	v_add_f32_e32 v0, v182, v0
	v_add_f32_e32 v0, v183, v0
	v_exp_f32_e32 v184, v48
	v_exp_f32_e32 v185, v49
	v_exp_f32_e32 v186, v50
	v_exp_f32_e32 v187, v51
	v_exp_f32_e32 v188, v52
	v_exp_f32_e32 v189, v53
	v_exp_f32_e32 v190, v54
	v_exp_f32_e32 v191, v55
	v_exp_f32_e32 v158, v56
	v_exp_f32_e32 v159, v57
	v_exp_f32_e32 v160, v58
	v_exp_f32_e32 v161, v59
	v_exp_f32_e32 v164, v60
	v_exp_f32_e32 v165, v61
	v_exp_f32_e32 v166, v62
	v_exp_f32_e32 v167, v63
	v_add_f32_e32 v0, v184, v0
	v_add_f32_e32 v0, v185, v0
	v_add_f32_e32 v0, v186, v0
	v_add_f32_e32 v0, v187, v0
	v_add_f32_e32 v0, v188, v0
	v_add_f32_e32 v0, v189, v0
	v_add_f32_e32 v0, v190, v0
	v_add_f32_e32 v0, v191, v0
	v_add_f32_e32 v0, v158, v0
	v_add_f32_e32 v0, v159, v0
	v_add_f32_e32 v0, v160, v0
	v_add_f32_e32 v0, v161, v0
	v_add_f32_e32 v0, v164, v0
	v_add_f32_e32 v0, v165, v0
	v_add_f32_e32 v0, v166, v0
	v_add_f32_e32 v0, v167, v0
	v_cmp_ge_f32_e32 vcc, s98, v0
	s_cmp_eq_u64 vcc, exec
	s_cbranch_scc1 .LBB0_537
; DI void attn_item(const Params& p, int item, char* smem) {
;     ...
;     { auto rr = __builtin_amdgcn_permlane32_swap(__float_as_uint(mx), __float_as_uint(mx), false, false);
;       mx = fmaxf(__uint_as_float(rr[0]), __uint_as_float(rr[1])); }
;     if (!__all(mx - mrun <= 8.f)) {
;       const float mn = fmaxf(mrun, mx);
;       const float alpha = __builtin_amdgcn_exp2f(mrun - mn);
;       mrun = mn; lrun *= alpha;
; #pragma unroll
;       for (int i = 0; i < 16; ++i) { o0[i] *= alpha; o1[i] *= alpha; }
;     }
;     float ps = 0.f;
; #pragma unroll
;     for (int i = 0; i < 16; ++i) { p0[i] = __builtin_amdgcn_exp2f(p0[i] - mrun); ps += p0[i]; }
; #pragma unroll
;     for (int i = 0; i < 16; ++i) { p1[i] = __builtin_amdgcn_exp2f(p1[i] - mrun); ps += p1[i]; }
	v_max_f32_e32 v10, v64, v65
	v_max3_f32 v10, v10, v66, v67
	v_max3_f32 v10, v10, v68, v69
	v_max3_f32 v10, v10, v70, v71
	v_max3_f32 v10, v10, v72, v73
	v_max3_f32 v10, v10, v74, v75
	v_max3_f32 v10, v10, v76, v77
	v_max3_f32 v10, v10, v78, v79
	v_max3_f32 v10, v10, v48, v49
	v_max3_f32 v10, v10, v50, v51
	v_max3_f32 v10, v10, v52, v53
	v_max3_f32 v10, v10, v54, v55
	v_max3_f32 v10, v10, v56, v57
	v_max3_f32 v10, v10, v58, v59
	v_max3_f32 v10, v10, v60, v61
	v_max3_f32 v10, v10, v62, v63
	v_mov_b32_e32 v11, v10
	s_nop 1
	v_permlane32_swap_b32_e32 v10, v11
	v_max_f32_e32 v10, v10, v11
	v_max_f32_e32 v11, s99, v10
	v_max_f32_e32 v10, 0, v11
	s_mov_b32 s98, 0x46000000
	v_exp_f32_e64 v10, -v10
	s_mov_b32 s99, 0
	v_sub_f32_e32 v196, v196, v11
	v_mul_f32_e32 v157, v157, v10
	v_pk_mul_f32 v[46:47], v[46:47], v[10:11] op_sel_hi:[1,0]
	v_pk_mul_f32 v[44:45], v[44:45], v[10:11] op_sel_hi:[1,0]
	v_pk_mul_f32 v[42:43], v[42:43], v[10:11] op_sel_hi:[1,0]
	v_pk_mul_f32 v[40:41], v[40:41], v[10:11] op_sel_hi:[1,0]
	v_pk_mul_f32 v[38:39], v[38:39], v[10:11] op_sel_hi:[1,0]
	v_pk_mul_f32 v[36:37], v[36:37], v[10:11] op_sel_hi:[1,0]
	v_pk_mul_f32 v[34:35], v[34:35], v[10:11] op_sel_hi:[1,0]
	v_pk_mul_f32 v[32:33], v[32:33], v[10:11] op_sel_hi:[1,0]
	v_pk_mul_f32 v[30:31], v[30:31], v[10:11] op_sel_hi:[1,0]
	v_pk_mul_f32 v[28:29], v[28:29], v[10:11] op_sel_hi:[1,0]
	v_pk_mul_f32 v[26:27], v[26:27], v[10:11] op_sel_hi:[1,0]
	v_pk_mul_f32 v[24:25], v[24:25], v[10:11] op_sel_hi:[1,0]
	v_pk_mul_f32 v[22:23], v[22:23], v[10:11] op_sel_hi:[1,0]
	v_pk_mul_f32 v[20:21], v[20:21], v[10:11] op_sel_hi:[1,0]
	v_pk_mul_f32 v[18:19], v[18:19], v[10:11] op_sel_hi:[1,0]
	v_pk_mul_f32 v[16:17], v[16:17], v[10:11] op_sel_hi:[1,0]
	v_mov_b32_e32 v197, v196
	v_mov_b32_e32 v198, v196
	v_mov_b32_e32 v199, v196
	v_mov_b32_e32 v200, v196
	v_mov_b32_e32 v201, v196
	v_mov_b32_e32 v202, v196
	v_mov_b32_e32 v203, v196
	v_mov_b32_e32 v204, v196
	v_mov_b32_e32 v205, v196
	v_mov_b32_e32 v206, v196
	v_mov_b32_e32 v207, v196
	v_mov_b32_e32 v208, v196
	v_mov_b32_e32 v209, v196
	v_mov_b32_e32 v210, v196
	v_mov_b32_e32 v211, v196
	v_sub_f32_e32 v64, v64, v11
	v_sub_f32_e32 v65, v65, v11
	v_sub_f32_e32 v66, v66, v11
	v_sub_f32_e32 v67, v67, v11
	v_sub_f32_e32 v68, v68, v11
	v_sub_f32_e32 v69, v69, v11
	v_sub_f32_e32 v70, v70, v11
	v_sub_f32_e32 v71, v71, v11
	v_sub_f32_e32 v72, v72, v11
	v_sub_f32_e32 v73, v73, v11
	v_sub_f32_e32 v74, v74, v11
	v_sub_f32_e32 v75, v75, v11
	v_sub_f32_e32 v76, v76, v11
	v_sub_f32_e32 v77, v77, v11
	v_sub_f32_e32 v78, v78, v11
	v_sub_f32_e32 v79, v79, v11
	v_sub_f32_e32 v48, v48, v11
	v_sub_f32_e32 v49, v49, v11
	v_sub_f32_e32 v50, v50, v11
	v_sub_f32_e32 v51, v51, v11
	v_sub_f32_e32 v52, v52, v11
	v_sub_f32_e32 v53, v53, v11
	v_sub_f32_e32 v54, v54, v11
	v_sub_f32_e32 v55, v55, v11
	v_sub_f32_e32 v56, v56, v11
	v_sub_f32_e32 v57, v57, v11
	v_sub_f32_e32 v58, v58, v11
	v_sub_f32_e32 v59, v59, v11
	v_sub_f32_e32 v60, v60, v11
	v_sub_f32_e32 v61, v61, v11
	v_sub_f32_e32 v62, v62, v11
	v_sub_f32_e32 v63, v63, v11
	v_exp_f32_e32 v168, v64
	v_exp_f32_e32 v169, v65
	v_exp_f32_e32 v170, v66
	v_exp_f32_e32 v171, v67
	v_exp_f32_e32 v172, v68
	v_exp_f32_e32 v173, v69
	v_exp_f32_e32 v174, v70
	v_exp_f32_e32 v175, v71
	v_exp_f32_e32 v176, v72
	v_exp_f32_e32 v177, v73
	v_exp_f32_e32 v178, v74
	v_exp_f32_e32 v179, v75
	v_exp_f32_e32 v180, v76
	v_exp_f32_e32 v181, v77
	v_exp_f32_e32 v182, v78
	v_exp_f32_e32 v183, v79
	v_exp_f32_e32 v184, v48
	v_exp_f32_e32 v185, v49
	v_exp_f32_e32 v186, v50
	v_exp_f32_e32 v187, v51
	v_exp_f32_e32 v188, v52
	v_exp_f32_e32 v189, v53
	v_exp_f32_e32 v190, v54
	v_exp_f32_e32 v191, v55
	v_exp_f32_e32 v158, v56
	v_exp_f32_e32 v159, v57
	v_exp_f32_e32 v160, v58
	v_exp_f32_e32 v161, v59
	v_exp_f32_e32 v164, v60
	v_exp_f32_e32 v165, v61
	v_exp_f32_e32 v166, v62
	v_exp_f32_e32 v167, v63
	v_add_f32_e32 v0, v168, v169
	v_add_f32_e32 v0, v170, v0
	v_add_f32_e32 v0, v171, v0
	v_add_f32_e32 v0, v172, v0
	v_add_f32_e32 v0, v173, v0
	v_add_f32_e32 v0, v174, v0
	v_add_f32_e32 v0, v175, v0
	v_add_f32_e32 v0, v176, v0
	v_add_f32_e32 v0, v177, v0
	v_add_f32_e32 v0, v178, v0
	v_add_f32_e32 v0, v179, v0
	v_add_f32_e32 v0, v180, v0
	v_add_f32_e32 v0, v181, v0
	v_add_f32_e32 v0, v182, v0
	v_add_f32_e32 v0, v183, v0
	v_add_f32_e32 v0, v184, v0
	v_add_f32_e32 v0, v185, v0
	v_add_f32_e32 v0, v186, v0
	v_add_f32_e32 v0, v187, v0
	v_add_f32_e32 v0, v188, v0
	v_add_f32_e32 v0, v189, v0
	v_add_f32_e32 v0, v190, v0
	v_add_f32_e32 v0, v191, v0
	v_add_f32_e32 v0, v158, v0
	v_add_f32_e32 v0, v159, v0
	v_add_f32_e32 v0, v160, v0
	v_add_f32_e32 v0, v161, v0
	v_add_f32_e32 v0, v164, v0
	v_add_f32_e32 v0, v165, v0
	v_add_f32_e32 v0, v166, v0
	v_add_f32_e32 v0, v167, v0
